# c13 + GDN diagonal-block inverse with v_pk_fma_f32 (row pairs, op_sel half broadcast) and paired bf16 cvt + ds_write_b16_d16_hi
# speedup vs baseline: 1.0024x; 1.0024x over previous
.Lgt_inv:
	v_cmp_gt_u32_e32 vcc, 16, v3
	s_and_saveexec_b64 s[10:11], vcc
	s_cbranch_execz .Lgt_invend
	v_mov_b32_e32 v119, s97
	ds_read_b128 v[120:123], v119 offset:0
	ds_read_b128 v[124:127], v119 offset:16
	ds_read_b128 v[128:131], v119 offset:32
	ds_read_b128 v[132:135], v119 offset:48
	ds_read_b128 v[142:145], v119 offset:80
	ds_read_b128 v[146:149], v119 offset:96
	ds_read_b128 v[150:153], v119 offset:112
	ds_read_b128 v[154:157], v119 offset:128
	ds_read_b128 v[158:161], v119 offset:160
	ds_read_b128 v[252:255], v119 offset:176
	ds_read_b128 v[108:111], v119 offset:192
	ds_read_b128 v[112:115], v119 offset:208
	ds_read_b128 v[210:213], v119 offset:256
	ds_read_b128 v[214:217], v119 offset:272
	ds_read_b128 v[164:167], v119 offset:288
	s_mov_b64 s[12:13], 0x1
	v_cndmask_b32_e64 v236, 0, 1.0, s[12:13]
	s_mov_b64 s[48:49], 0x2
	v_cndmask_b32_e64 v237, 0, 1.0, s[48:49]
	s_mov_b64 s[50:51], 0x4
	v_cndmask_b32_e64 v238, 0, 1.0, s[50:51]
	s_mov_b64 s[12:13], 0x8
	v_cndmask_b32_e64 v239, 0, 1.0, s[12:13]
	s_mov_b64 s[48:49], 0x10
	v_cndmask_b32_e64 v240, 0, 1.0, s[48:49]
	s_mov_b64 s[50:51], 0x20
	v_cndmask_b32_e64 v241, 0, 1.0, s[50:51]
	s_mov_b64 s[12:13], 0x40
	v_cndmask_b32_e64 v242, 0, 1.0, s[12:13]
	s_mov_b64 s[48:49], 0x80
	v_cndmask_b32_e64 v243, 0, 1.0, s[48:49]
	s_mov_b64 s[50:51], 0x100
	v_cndmask_b32_e64 v244, 0, 1.0, s[50:51]
	s_mov_b64 s[12:13], 0x200
	v_cndmask_b32_e64 v245, 0, 1.0, s[12:13]
	s_mov_b64 s[48:49], 0x400
	v_cndmask_b32_e64 v246, 0, 1.0, s[48:49]
	s_mov_b64 s[50:51], 0x800
	v_cndmask_b32_e64 v247, 0, 1.0, s[50:51]
	s_mov_b64 s[12:13], 0x1000
	v_cndmask_b32_e64 v248, 0, 1.0, s[12:13]
	s_mov_b64 s[48:49], 0x2000
	v_cndmask_b32_e64 v249, 0, 1.0, s[48:49]
	s_mov_b64 s[50:51], 0x4000
	v_cndmask_b32_e64 v250, 0, 1.0, s[50:51]
	s_mov_b64 s[12:13], 0x8000
	v_cndmask_b32_e64 v251, 0, 1.0, s[12:13]
	s_waitcnt lgkmcnt(11)
	v_fma_f32 v237, -v121, v236, v237
	v_pk_fma_f32 v[238:239], v[122:123], v[236:237], v[238:239] op_sel_hi:[1,0,1] neg_lo:[1,0,0] neg_hi:[1,0,0]
	v_pk_fma_f32 v[240:241], v[124:125], v[236:237], v[240:241] op_sel_hi:[1,0,1] neg_lo:[1,0,0] neg_hi:[1,0,0]
	v_pk_fma_f32 v[242:243], v[126:127], v[236:237], v[242:243] op_sel_hi:[1,0,1] neg_lo:[1,0,0] neg_hi:[1,0,0]
	v_pk_fma_f32 v[244:245], v[128:129], v[236:237], v[244:245] op_sel_hi:[1,0,1] neg_lo:[1,0,0] neg_hi:[1,0,0]
	v_pk_fma_f32 v[246:247], v[130:131], v[236:237], v[246:247] op_sel_hi:[1,0,1] neg_lo:[1,0,0] neg_hi:[1,0,0]
	v_pk_fma_f32 v[248:249], v[132:133], v[236:237], v[248:249] op_sel_hi:[1,0,1] neg_lo:[1,0,0] neg_hi:[1,0,0]
	v_pk_fma_f32 v[250:251], v[134:135], v[236:237], v[250:251] op_sel_hi:[1,0,1] neg_lo:[1,0,0] neg_hi:[1,0,0]
	ds_read_b128 v[120:123], v119 offset:336
	ds_read_b128 v[124:127], v119 offset:352
	ds_read_b128 v[128:131], v119 offset:368
	ds_read_b128 v[132:135], v119 offset:416
	s_waitcnt lgkmcnt(11)
	v_pk_fma_f32 v[238:239], v[144:145], v[236:237], v[238:239] op_sel:[0,1,0] op_sel_hi:[1,1,1] neg_lo:[1,0,0] neg_hi:[1,0,0]
	v_pk_fma_f32 v[240:241], v[146:147], v[236:237], v[240:241] op_sel:[0,1,0] op_sel_hi:[1,1,1] neg_lo:[1,0,0] neg_hi:[1,0,0]
	v_pk_fma_f32 v[242:243], v[148:149], v[236:237], v[242:243] op_sel:[0,1,0] op_sel_hi:[1,1,1] neg_lo:[1,0,0] neg_hi:[1,0,0]
	v_pk_fma_f32 v[244:245], v[150:151], v[236:237], v[244:245] op_sel:[0,1,0] op_sel_hi:[1,1,1] neg_lo:[1,0,0] neg_hi:[1,0,0]
	v_pk_fma_f32 v[246:247], v[152:153], v[236:237], v[246:247] op_sel:[0,1,0] op_sel_hi:[1,1,1] neg_lo:[1,0,0] neg_hi:[1,0,0]
	v_pk_fma_f32 v[248:249], v[154:155], v[236:237], v[248:249] op_sel:[0,1,0] op_sel_hi:[1,1,1] neg_lo:[1,0,0] neg_hi:[1,0,0]
	v_pk_fma_f32 v[250:251], v[156:157], v[236:237], v[250:251] op_sel:[0,1,0] op_sel_hi:[1,1,1] neg_lo:[1,0,0] neg_hi:[1,0,0]
	ds_read_b128 v[142:145], v119 offset:432
	ds_read_b128 v[146:149], v119 offset:448
	ds_read_b128 v[150:153], v119 offset:496
	ds_read_b128 v[154:157], v119 offset:512
	s_waitcnt lgkmcnt(11)
	v_fma_f32 v239, -v161, v238, v239
	v_pk_fma_f32 v[240:241], v[252:253], v[238:239], v[240:241] op_sel_hi:[1,0,1] neg_lo:[1,0,0] neg_hi:[1,0,0]
	v_pk_fma_f32 v[242:243], v[254:255], v[238:239], v[242:243] op_sel_hi:[1,0,1] neg_lo:[1,0,0] neg_hi:[1,0,0]
	v_pk_fma_f32 v[244:245], v[108:109], v[238:239], v[244:245] op_sel_hi:[1,0,1] neg_lo:[1,0,0] neg_hi:[1,0,0]
	v_pk_fma_f32 v[246:247], v[110:111], v[238:239], v[246:247] op_sel_hi:[1,0,1] neg_lo:[1,0,0] neg_hi:[1,0,0]
	v_pk_fma_f32 v[248:249], v[112:113], v[238:239], v[248:249] op_sel_hi:[1,0,1] neg_lo:[1,0,0] neg_hi:[1,0,0]
	v_pk_fma_f32 v[250:251], v[114:115], v[238:239], v[250:251] op_sel_hi:[1,0,1] neg_lo:[1,0,0] neg_hi:[1,0,0]
	ds_read_b128 v[158:161], v119 offset:528
	ds_read_b128 v[252:255], v119 offset:592
	ds_read_b128 v[108:111], v119 offset:608
	ds_read_b128 v[112:115], v119 offset:672
	s_waitcnt lgkmcnt(12)
	v_pk_fma_f32 v[240:241], v[210:211], v[238:239], v[240:241] op_sel:[0,1,0] op_sel_hi:[1,1,1] neg_lo:[1,0,0] neg_hi:[1,0,0]
	v_pk_fma_f32 v[242:243], v[212:213], v[238:239], v[242:243] op_sel:[0,1,0] op_sel_hi:[1,1,1] neg_lo:[1,0,0] neg_hi:[1,0,0]
	v_pk_fma_f32 v[244:245], v[214:215], v[238:239], v[244:245] op_sel:[0,1,0] op_sel_hi:[1,1,1] neg_lo:[1,0,0] neg_hi:[1,0,0]
	v_pk_fma_f32 v[246:247], v[216:217], v[238:239], v[246:247] op_sel:[0,1,0] op_sel_hi:[1,1,1] neg_lo:[1,0,0] neg_hi:[1,0,0]
	v_pk_fma_f32 v[248:249], v[164:165], v[238:239], v[248:249] op_sel:[0,1,0] op_sel_hi:[1,1,1] neg_lo:[1,0,0] neg_hi:[1,0,0]
	v_pk_fma_f32 v[250:251], v[166:167], v[238:239], v[250:251] op_sel:[0,1,0] op_sel_hi:[1,1,1] neg_lo:[1,0,0] neg_hi:[1,0,0]
	ds_read_b128 v[210:213], v119 offset:688
	ds_read_b128 v[214:217], v119 offset:752
	ds_read_b128 v[164:167], v119 offset:768
	s_waitcnt lgkmcnt(12)
	v_fma_f32 v241, -v121, v240, v241
	v_pk_fma_f32 v[242:243], v[122:123], v[240:241], v[242:243] op_sel_hi:[1,0,1] neg_lo:[1,0,0] neg_hi:[1,0,0]
	v_pk_fma_f32 v[244:245], v[124:125], v[240:241], v[244:245] op_sel_hi:[1,0,1] neg_lo:[1,0,0] neg_hi:[1,0,0]
	v_pk_fma_f32 v[246:247], v[126:127], v[240:241], v[246:247] op_sel_hi:[1,0,1] neg_lo:[1,0,0] neg_hi:[1,0,0]
	v_pk_fma_f32 v[248:249], v[128:129], v[240:241], v[248:249] op_sel_hi:[1,0,1] neg_lo:[1,0,0] neg_hi:[1,0,0]
	v_pk_fma_f32 v[250:251], v[130:131], v[240:241], v[250:251] op_sel_hi:[1,0,1] neg_lo:[1,0,0] neg_hi:[1,0,0]
	ds_read_b128 v[120:123], v119 offset:832
	ds_read_b128 v[124:127], v119 offset:848
	ds_read_b128 v[128:131], v119 offset:928
	s_waitcnt lgkmcnt(12)
	v_pk_fma_f32 v[242:243], v[134:135], v[240:241], v[242:243] op_sel:[0,1,0] op_sel_hi:[1,1,1] neg_lo:[1,0,0] neg_hi:[1,0,0]
	v_pk_fma_f32 v[244:245], v[142:143], v[240:241], v[244:245] op_sel:[0,1,0] op_sel_hi:[1,1,1] neg_lo:[1,0,0] neg_hi:[1,0,0]
	v_pk_fma_f32 v[246:247], v[144:145], v[240:241], v[246:247] op_sel:[0,1,0] op_sel_hi:[1,1,1] neg_lo:[1,0,0] neg_hi:[1,0,0]
	v_pk_fma_f32 v[248:249], v[146:147], v[240:241], v[248:249] op_sel:[0,1,0] op_sel_hi:[1,1,1] neg_lo:[1,0,0] neg_hi:[1,0,0]
	v_pk_fma_f32 v[250:251], v[148:149], v[240:241], v[250:251] op_sel:[0,1,0] op_sel_hi:[1,1,1] neg_lo:[1,0,0] neg_hi:[1,0,0]
	ds_read_b128 v[132:135], v119 offset:1008
	ds_read_b128 v[142:145], v119 offset:1088
	ds_read_b128 v[146:149], v119 offset:1168
	s_waitcnt lgkmcnt(12)
	v_fma_f32 v243, -v153, v242, v243
	v_pk_fma_f32 v[244:245], v[154:155], v[242:243], v[244:245] op_sel_hi:[1,0,1] neg_lo:[1,0,0] neg_hi:[1,0,0]
	v_pk_fma_f32 v[246:247], v[156:157], v[242:243], v[246:247] op_sel_hi:[1,0,1] neg_lo:[1,0,0] neg_hi:[1,0,0]
	v_pk_fma_f32 v[248:249], v[158:159], v[242:243], v[248:249] op_sel_hi:[1,0,1] neg_lo:[1,0,0] neg_hi:[1,0,0]
	v_pk_fma_f32 v[250:251], v[160:161], v[242:243], v[250:251] op_sel_hi:[1,0,1] neg_lo:[1,0,0] neg_hi:[1,0,0]
	s_waitcnt lgkmcnt(10)
	v_pk_fma_f32 v[244:245], v[252:253], v[242:243], v[244:245] op_sel:[0,1,0] op_sel_hi:[1,1,1] neg_lo:[1,0,0] neg_hi:[1,0,0]
	v_pk_fma_f32 v[246:247], v[254:255], v[242:243], v[246:247] op_sel:[0,1,0] op_sel_hi:[1,1,1] neg_lo:[1,0,0] neg_hi:[1,0,0]
	v_pk_fma_f32 v[248:249], v[108:109], v[242:243], v[248:249] op_sel:[0,1,0] op_sel_hi:[1,1,1] neg_lo:[1,0,0] neg_hi:[1,0,0]
	v_pk_fma_f32 v[250:251], v[110:111], v[242:243], v[250:251] op_sel:[0,1,0] op_sel_hi:[1,1,1] neg_lo:[1,0,0] neg_hi:[1,0,0]
	s_waitcnt lgkmcnt(8)
	v_fma_f32 v245, -v113, v244, v245
	v_pk_fma_f32 v[246:247], v[114:115], v[244:245], v[246:247] op_sel_hi:[1,0,1] neg_lo:[1,0,0] neg_hi:[1,0,0]
	v_pk_fma_f32 v[248:249], v[210:211], v[244:245], v[248:249] op_sel_hi:[1,0,1] neg_lo:[1,0,0] neg_hi:[1,0,0]
	v_pk_fma_f32 v[250:251], v[212:213], v[244:245], v[250:251] op_sel_hi:[1,0,1] neg_lo:[1,0,0] neg_hi:[1,0,0]
	s_waitcnt lgkmcnt(6)
	v_pk_fma_f32 v[246:247], v[216:217], v[244:245], v[246:247] op_sel:[0,1,0] op_sel_hi:[1,1,1] neg_lo:[1,0,0] neg_hi:[1,0,0]
	v_pk_fma_f32 v[248:249], v[164:165], v[244:245], v[248:249] op_sel:[0,1,0] op_sel_hi:[1,1,1] neg_lo:[1,0,0] neg_hi:[1,0,0]
	v_pk_fma_f32 v[250:251], v[166:167], v[244:245], v[250:251] op_sel:[0,1,0] op_sel_hi:[1,1,1] neg_lo:[1,0,0] neg_hi:[1,0,0]
	s_waitcnt lgkmcnt(4)
	v_fma_f32 v247, -v123, v246, v247
	v_pk_fma_f32 v[248:249], v[124:125], v[246:247], v[248:249] op_sel_hi:[1,0,1] neg_lo:[1,0,0] neg_hi:[1,0,0]
	v_pk_fma_f32 v[250:251], v[126:127], v[246:247], v[250:251] op_sel_hi:[1,0,1] neg_lo:[1,0,0] neg_hi:[1,0,0]
	s_waitcnt lgkmcnt(3)
	v_pk_fma_f32 v[248:249], v[128:129], v[246:247], v[248:249] op_sel:[0,1,0] op_sel_hi:[1,1,1] neg_lo:[1,0,0] neg_hi:[1,0,0]
	v_pk_fma_f32 v[250:251], v[130:131], v[246:247], v[250:251] op_sel:[0,1,0] op_sel_hi:[1,1,1] neg_lo:[1,0,0] neg_hi:[1,0,0]
	s_waitcnt lgkmcnt(2)
	v_fma_f32 v249, -v133, v248, v249
	v_pk_fma_f32 v[250:251], v[134:135], v[248:249], v[250:251] op_sel_hi:[1,0,1] neg_lo:[1,0,0] neg_hi:[1,0,0]
	s_waitcnt lgkmcnt(1)
	v_pk_fma_f32 v[250:251], v[144:145], v[248:249], v[250:251] op_sel:[0,1,0] op_sel_hi:[1,1,1] neg_lo:[1,0,0] neg_hi:[1,0,0]
	s_waitcnt lgkmcnt(0)
	v_fma_f32 v251, -v149, v250, v251
	v_lshl_add_u32 v169, v3, 1, s88
	v_cvt_pk_bf16_f32 v170, v236, v237
	ds_write_b16 v169, v170 offset:0
	ds_write_b16_d16_hi v169, v170 offset:40
	v_cvt_pk_bf16_f32 v171, v238, v239
	ds_write_b16 v169, v171 offset:80
	ds_write_b16_d16_hi v169, v171 offset:120
	v_cvt_pk_bf16_f32 v170, v240, v241
	ds_write_b16 v169, v170 offset:160
	ds_write_b16_d16_hi v169, v170 offset:200
	v_cvt_pk_bf16_f32 v171, v242, v243
	ds_write_b16 v169, v171 offset:240
	ds_write_b16_d16_hi v169, v171 offset:280
	v_cvt_pk_bf16_f32 v170, v244, v245
	ds_write_b16 v169, v170 offset:320
	ds_write_b16_d16_hi v169, v170 offset:360
	v_cvt_pk_bf16_f32 v171, v246, v247
	ds_write_b16 v169, v171 offset:400
	ds_write_b16_d16_hi v169, v171 offset:440
	v_cvt_pk_bf16_f32 v170, v248, v249
	ds_write_b16 v169, v170 offset:480
	ds_write_b16_d16_hi v169, v170 offset:520
	v_cvt_pk_bf16_f32 v171, v250, v251
	ds_write_b16 v169, v171 offset:560
	ds_write_b16_d16_hi v169, v171 offset:600
